# grid barrier (8 in-loop instances): leader protocol hand-written -- round number kept in a lane instead of two integer divisions, no timeout bookkeeping, release polls pipelined 4 deep with spacing
# speedup vs baseline: 1.0119x; 1.0119x over previous
_Z10hybrid_fwd6Params:
	s_mov_b32 s100, 2
	s_nop 0
	v_writelane_b32 v255, s100, 21
	s_load_dwordx2 s[42:43], s[0:1], 0xb8
	s_mov_b64 s[78:79], s[0:1]
	s_add_u32 s0, s78, 0xb8
	s_addc_u32 s1, s79, 0
	v_and_b32_e32 v1, 0x3ff, v0
	s_waitcnt lgkmcnt(0)
	s_and_b32 s3, s42, 7
	v_readfirstlane_b32 s38, v1
	s_cmp_lg_u32 s3, 0
	s_mov_b32 s41, s2
	s_cbranch_scc1 .LBB0_2
	s_ashr_i32 s4, s2, 31
	s_lshr_b32 s4, s4, 29
	s_add_i32 s4, s2, s4
	s_and_b32 s5, s4, -8
	s_ashr_i32 s3, s42, 3
	s_sub_i32 s5, s2, s5
	s_mul_i32 s3, s3, s5
	s_ashr_i32 s4, s4, 3
	s_add_i32 s41, s3, s4

.LBB0_214:
	s_waitcnt vmcnt(0)
	s_waitcnt vmcnt(0) lgkmcnt(0)
	s_barrier
	s_and_saveexec_b64 s[40:41], s[4:5]
	s_cbranch_execz .LBB0_258
	s_waitcnt vmcnt(0) expcnt(0) lgkmcnt(0)
	s_getreg_b32 s6, hwreg(HW_REG_XCC_ID, 0, 4)
	v_readlane_b32 s14, v254, 42
	v_readlane_b32 s7, v255, 21
	s_and_b32 s6, s6, 15
	v_mov_b32_e32 v2, s14
	ds_read_b32 v3, v2
	ds_read_b32 v4, v2 offset:4
	s_lshl_b32 s6, s6, 8
	s_add_i32 s10, s7, 1
	s_add_u32 s14, s6, 0x5400
	v_mov_b32_e32 v2, s14
	global_atomic_add v5, v2, v222, s[46:47] sc0
	v_writelane_b32 v255, s10, 21
	s_waitcnt lgkmcnt(0)
	v_readfirstlane_b32 s8, v3
	v_readfirstlane_b32 s9, v4
	s_nop 0
	s_mul_i32 s11, s10, s8
	s_mul_i32 s12, s10, s9
	s_waitcnt vmcnt(0)
	v_readfirstlane_b32 s15, v5
	s_nop 0
	s_add_i32 s15, s15, 1
	s_cmp_eq_u32 s15, s11
	s_cbranch_scc0 .Lgb258_local
	buffer_wbl2 sc1
	s_waitcnt vmcnt(0)
	v_mov_b32_e32 v3, 0x7400
	global_atomic_add v5, v3, v222, s[46:47] sc0
	s_waitcnt vmcnt(0)
	v_readfirstlane_b32 s15, v5
	v_mov_b32_e32 v3, 0x7500
	s_add_i32 s15, s15, 1
	s_cmp_eq_u32 s15, s12
	s_cbranch_scc0 .Lgb258_topw
	global_atomic_add v3, v222, s[46:47]
	s_branch .Lgb258_toprel
.Lgb258_topw:
	s_mov_b32 s16, 0x10000
	global_load_dword v6, v3, s[46:47] sc1
	s_sleep 10
	global_load_dword v7, v3, s[46:47] sc1
	s_sleep 10
	global_load_dword v8, v3, s[46:47] sc1
	s_sleep 10
.Lgb258t_spin:
	global_load_dword v9, v3, s[46:47] sc1
	s_waitcnt vmcnt(3)
	v_readfirstlane_b32 s17, v6
	s_nop 0
	s_cmp_lg_u32 s17, s7
	s_cbranch_scc1 .Lgb258t_out
	s_sleep 10
	global_load_dword v6, v3, s[46:47] sc1
	s_waitcnt vmcnt(3)
	v_readfirstlane_b32 s17, v7
	s_nop 0
	s_cmp_lg_u32 s17, s7
	s_cbranch_scc1 .Lgb258t_out
	s_sleep 10
	global_load_dword v7, v3, s[46:47] sc1
	s_waitcnt vmcnt(3)
	v_readfirstlane_b32 s17, v8
	s_nop 0
	s_cmp_lg_u32 s17, s7
	s_cbranch_scc1 .Lgb258t_out
	s_sleep 10
	global_load_dword v8, v3, s[46:47] sc1
	s_waitcnt vmcnt(3)
	v_readfirstlane_b32 s17, v9
	s_nop 0
	s_cmp_lg_u32 s17, s7
	s_cbranch_scc1 .Lgb258t_out
	s_sleep 10
	s_sub_u32 s16, s16, 1
	s_cmp_lg_u32 s16, 0
	s_cbranch_scc1 .Lgb258t_spin
.Lgb258t_out:
.Lgb258_toprel:
	s_waitcnt vmcnt(0)
	buffer_inv sc1
	s_add_u32 s14, s6, 0x6400
	v_mov_b32_e32 v2, s14
	global_atomic_add v2, v222, s[46:47]
	s_waitcnt vmcnt(0)
	s_branch .Lgb258_done
.Lgb258_local:
	s_add_u32 s14, s6, 0x6400
	v_mov_b32_e32 v3, s14
	s_mov_b32 s16, 0x10000
	global_load_dword v6, v3, s[46:47] sc1
	s_sleep 4
	global_load_dword v7, v3, s[46:47] sc1
	s_sleep 4
	global_load_dword v8, v3, s[46:47] sc1
	s_sleep 4
.Lgb258l_spin:
	global_load_dword v9, v3, s[46:47] sc1
	s_waitcnt vmcnt(3)
	v_readfirstlane_b32 s17, v6
	s_nop 0
	s_cmp_lg_u32 s17, s7
	s_cbranch_scc1 .Lgb258l_out
	s_sleep 4
	global_load_dword v6, v3, s[46:47] sc1
	s_waitcnt vmcnt(3)
	v_readfirstlane_b32 s17, v7
	s_nop 0
	s_cmp_lg_u32 s17, s7
	s_cbranch_scc1 .Lgb258l_out
	s_sleep 4
	global_load_dword v7, v3, s[46:47] sc1
	s_waitcnt vmcnt(3)
	v_readfirstlane_b32 s17, v8
	s_nop 0
	s_cmp_lg_u32 s17, s7
	s_cbranch_scc1 .Lgb258l_out
	s_sleep 4
	global_load_dword v8, v3, s[46:47] sc1
	s_waitcnt vmcnt(3)
	v_readfirstlane_b32 s17, v9
	s_nop 0
	s_cmp_lg_u32 s17, s7
	s_cbranch_scc1 .Lgb258l_out
	s_sleep 4
	s_sub_u32 s16, s16, 1
	s_cmp_lg_u32 s16, 0
	s_cbranch_scc1 .Lgb258l_spin
.Lgb258l_out:
	s_waitcnt vmcnt(0)
	buffer_inv sc1
	s_waitcnt vmcnt(0)
.Lgb258_done:
.LBB0_258:
	s_or_b64 exec, exec, s[40:41]
	s_xor_b64 s[4:5], s[38:39], -1
	v_writelane_b32 v254, s4, 53
	s_waitcnt lgkmcnt(0)
	s_barrier
	v_writelane_b32 v254, s5, 54
	s_nop 0
	v_readlane_b32 s4, v254, 47
	v_readlane_b32 s5, v254, 48
	s_xor_b64 s[4:5], s[4:5], -1
	v_writelane_b32 v254, s4, 55
	s_nop 1
	v_writelane_b32 v254, s5, 56
	v_readlane_b32 s6, v255, 10
	s_nop 0
	s_cmp_eq_u32 s6, 1
	s_cbranch_scc0 .Lp1_to_p2
	s_mov_b32 s6, 0
	s_nop 0
	v_writelane_b32 v255, s6, 10
	s_cmp_lt_u32 s2, 0x98
	s_cbranch_scc0 .Lp1_to_p2
	s_mov_b32 s6, 2
	s_nop 0
	v_writelane_b32 v255, s6, 10
	s_add_i32 s14, s2, 0x100
	s_branch .Lp1_pass

.LBB0_325:
	s_waitcnt vmcnt(0)
	s_waitcnt lgkmcnt(0)
	s_barrier
	s_and_saveexec_b64 s[40:41], s[4:5]
	s_cbranch_execz .LBB0_369
	s_waitcnt vmcnt(0) expcnt(0) lgkmcnt(0)
	s_getreg_b32 s6, hwreg(HW_REG_XCC_ID, 0, 4)
	v_readlane_b32 s14, v254, 42
	v_readlane_b32 s7, v255, 21
	s_and_b32 s6, s6, 15
	v_mov_b32_e32 v2, s14
	ds_read_b32 v3, v2
	ds_read_b32 v4, v2 offset:4
	s_lshl_b32 s6, s6, 8
	s_add_i32 s10, s7, 1
	s_add_u32 s14, s6, 0x5400
	v_mov_b32_e32 v2, s14
	global_atomic_add v5, v2, v222, s[46:47] sc0
	v_writelane_b32 v255, s10, 21
	s_waitcnt lgkmcnt(0)
	v_readfirstlane_b32 s8, v3
	v_readfirstlane_b32 s9, v4
	s_nop 0
	s_mul_i32 s11, s10, s8
	s_mul_i32 s12, s10, s9
	s_waitcnt vmcnt(0)
	v_readfirstlane_b32 s15, v5
	s_nop 0
	s_add_i32 s15, s15, 1
	s_cmp_eq_u32 s15, s11
	s_cbranch_scc0 .Lgb369_local
	buffer_wbl2 sc1
	s_waitcnt vmcnt(0)
	v_mov_b32_e32 v3, 0x7400
	global_atomic_add v5, v3, v222, s[46:47] sc0
	s_waitcnt vmcnt(0)
	v_readfirstlane_b32 s15, v5
	v_mov_b32_e32 v3, 0x7500
	s_add_i32 s15, s15, 1
	s_cmp_eq_u32 s15, s12
	s_cbranch_scc0 .Lgb369_topw
	global_atomic_add v3, v222, s[46:47]
	s_branch .Lgb369_toprel

.Lgb369_done:
.LBB0_369:
	s_or_b64 exec, exec, s[40:41]
	v_readlane_b32 s4, v252, 6
	s_nop 0
	s_bitcmp1_b32 s4, 0
	s_cbranch_scc0 .Lp3_attn
	s_waitcnt lgkmcnt(0)
	s_barrier
	s_branch .Lp3_fix_entry

.Lgb603_done:
.LBB0_603:
	s_or_b64 exec, exec, s[40:41]
	s_mul_i32 s12, s71, 0x7800
	s_lshl_b64 s[4:5], s[12:13], 2
	v_readlane_b32 s6, v252, 9
	v_readlane_b32 s7, v252, 10
	s_add_u32 s4, s6, s4
	s_addc_u32 s5, s7, s5
	v_writelane_b32 v254, s4, 57
	v_readlane_b32 s6, v253, 0
	v_readlane_b32 s7, v253, 1
	v_writelane_b32 v254, s5, 58
	s_mul_i32 s12, s71, 0x4400
	v_readlane_b32 s4, v254, 51
	s_add_u32 s40, s4, 0x300000
	v_readlane_b32 s4, v254, 52
	s_addc_u32 s41, s4, 0
	s_lshl_b32 s10, s71, 2
	s_mul_i32 s4, s71, 0x110000
	s_add_u32 s4, s6, s4
	s_addc_u32 s5, s7, 0
	v_writelane_b32 v254, s4, 59
	v_readlane_b32 s8, v253, 2
	v_readlane_b32 s9, v253, 3
	v_writelane_b32 v254, s5, 60
	s_lshl_b64 s[4:5], s[12:13], 2
	s_add_u32 s21, s8, s4
	s_addc_u32 s4, s9, s5
	v_writelane_b32 v254, s4, 61
	s_or_b32 s4, s10, 1
	s_mul_i32 s5, s4, 0x44000
	v_writelane_b32 v254, s10, 63
	s_add_u32 s34, s6, s5
	s_mul_i32 s12, s4, 0x1100
	s_addc_u32 s35, s7, 0
	s_lshl_b64 s[4:5], s[12:13], 2
	v_readlane_b32 s6, v254, 53
	s_add_u32 s15, s8, s4
	v_readlane_b32 s7, v254, 54
	s_addc_u32 s16, s9, s5
	s_and_b64 vcc, exec, s[6:7]
	v_readlane_b32 s6, v253, 6
	v_readlane_b32 s7, v253, 7
	s_mov_b64 s[4:5], -1
	s_mov_b32 s71, 0x400000
	v_cndmask_b32_e64 v0, 0, 1, s[6:7]
	v_cmp_ne_u32_e64 s[6:7], 1, v0
	s_waitcnt lgkmcnt(0)
	s_barrier
	v_writelane_b32 v255, s6, 0
	s_nop 1
	v_writelane_b32 v255, s7, 1
	s_cbranch_vccz .LBB0_708
	v_readlane_b32 s4, v255, 0
	v_mbcnt_lo_u32_b32 v0, -1, 0
	v_mbcnt_hi_u32_b32 v0, -1, v0
	v_readlane_b32 s5, v255, 1
	v_add_u32_e32 v216, s33, v0
	s_and_b64 vcc, exec, s[4:5]
	v_readfirstlane_b32 s19, v216
	s_cbranch_vccnz .LBB0_707
	v_lshlrev_b32_e32 v0, 4, v216
	s_waitcnt vmcnt(0)
	v_add_u32_e32 v3, 0x2000, v0
	v_ashrrev_i32_e32 v2, 31, v3
	v_lshrrev_b32_e32 v2, 22, v2
	v_add_u32_e32 v2, v3, v2
	v_ashrrev_i32_e32 v2, 10, v2
	v_mul_i32_i24_e32 v4, 0x400, v2
	v_sub_u32_e32 v3, v3, v4
	v_lshrrev_b32_e32 v4, 4, v3
	v_bitop3_b32 v4, v4, v3, 32 bitop3:0x6c
	v_ashrrev_i32_e32 v3, 31, v4
	v_lshrrev_b32_e32 v3, 26, v3
	v_add_u32_e32 v5, v4, v3
	v_lshlrev_b32_e32 v6, 3, v2
	v_ashrrev_i32_e32 v3, 6, v5
	v_and_b32_e32 v6, -16, v6
	v_add_u32_e32 v6, v3, v6
	v_and_b32_e32 v7, 3, v3
	s_mov_b32 s4, 0x1fffe0
	v_lshrrev_b32_e32 v8, 2, v6
	v_lshlrev_b32_e32 v9, 1, v6
	v_and_b32_e32 v5, 0xc0, v5
	v_and_or_b32 v7, v6, s4, v7
	v_and_b32_e32 v8, 4, v8
	v_and_b32_e32 v9, 24, v9
	v_sub_u32_e32 v4, v4, v5
	v_or3_b32 v7, v7, v8, v9
	v_lshlrev_b32_e32 v8, 5, v2
	v_ashrrev_i16_sdwa v4, v222, sext(v4) dst_sel:DWORD dst_unused:UNUSED_PAD src0_sel:DWORD src1_sel:BYTE_0
	v_and_b32_e32 v8, 32, v8
	v_bfe_i32 v4, v4, 0, 16
	v_add_lshl_u32 v5, v8, v4, 1
	v_lshl_add_u32 v132, v7, 11, v5
	v_lshl_add_u32 v134, v6, 11, v5
	v_bfe_i32 v5, v216, 27, 1
	v_lshrrev_b32_e32 v5, 22, v5
	v_add_u32_e32 v5, v0, v5
	v_and_b32_e32 v5, 0xfffffc00, v5
	v_sub_u32_e32 v0, v0, v5
	v_lshrrev_b32_e32 v5, 4, v0
	v_ashrrev_i32_e32 v6, 31, v216
	v_bitop3_b32 v0, v5, v0, 32 bitop3:0x6c
	v_lshrrev_b32_e32 v6, 26, v6
	v_ashrrev_i32_e32 v5, 31, v0
	v_add_u32_e32 v6, v216, v6
	v_lshrrev_b32_e32 v5, 26, v5
	v_ashrrev_i32_e32 v6, 6, v6
	v_add_u32_e32 v7, v0, v5
	v_lshlrev_b32_e32 v8, 3, v6
	v_ashrrev_i32_e32 v5, 6, v7
	v_and_b32_e32 v8, -16, v8
	v_add_u32_e32 v8, v5, v8
	v_and_b32_e32 v9, 3, v5
	v_lshrrev_b32_e32 v10, 2, v8
	v_lshlrev_b32_e32 v11, 1, v8
	v_and_b32_e32 v7, 0xc0, v7
	s_ashr_i32 s8, s19, 6
	v_and_or_b32 v9, v8, s4, v9
	v_and_b32_e32 v10, 4, v10
	v_and_b32_e32 v11, 24, v11
	v_sub_u32_e32 v0, v0, v7
	s_ashr_i32 s36, s19, 8
	s_lshl_b32 s38, s8, 10
	v_or3_b32 v9, v9, v10, v11
	v_lshlrev_b32_e32 v10, 5, v6
	v_ashrrev_i16_sdwa v0, v222, sext(v0) dst_sel:DWORD dst_unused:UNUSED_PAD src0_sel:DWORD src1_sel:BYTE_0
	v_readlane_b32 s4, v253, 56
	v_and_b32_e32 v10, 32, v10
	v_bfe_i32 v7, v0, 0, 16
	v_readlane_b32 s5, v253, 57
	s_add_u32 s4, s40, s4
	v_add_lshl_u32 v10, v10, v7, 1
	s_addc_u32 s5, s41, s5
	s_add_i32 s71, s38, 0
	v_lshl_add_u32 v0, v9, 11, v10
	s_add_i32 m0, s71, 0x10000
	v_lshl_add_u32 v136, v8, 11, v10
	global_load_lds_dwordx4 v0, s[4:5]
	s_add_i32 m0, s71, 0x12000
	s_add_u32 s6, s4, 0x40000
	global_load_lds_dwordx4 v132, s[4:5]
	s_addc_u32 s7, s5, 0
	s_add_i32 m0, s71, 0x14000
	s_add_i32 s39, s71, 0x2000
	global_load_lds_dwordx4 v0, s[6:7]
	s_add_i32 m0, s71, 0x16000
	s_add_i32 s37, s71, 0x4000
	global_load_lds_dwordx4 v132, s[6:7]
	v_readlane_b32 s6, v253, 58
	s_mov_b32 m0, s71
	v_readlane_b32 s7, v253, 59
	s_add_i32 s14, s71, 0x6000
	v_writelane_b32 v255, s21, 2
	v_writelane_b32 v255, s16, 3
	v_writelane_b32 v255, s15, 4
	v_writelane_b32 v255, s34, 5
	global_load_lds_dwordx4 v136, s[6:7]
	s_mov_b32 m0, s39
	v_writelane_b32 v255, s35, 6
	global_load_lds_dwordx4 v134, s[6:7]
	v_readlane_b32 s6, v253, 60
	s_mov_b32 m0, s37
	v_readlane_b32 s7, v253, 61
	s_cmp_lg_u32 s36, 1
	s_nop 3
	global_load_lds_dwordx4 v136, s[6:7]
	s_mov_b32 m0, s14
	s_nop 0
	global_load_lds_dwordx4 v134, s[6:7]
	s_cbranch_scc1 .LBB0_607
	s_barrier

.LBB0_833:
	s_waitcnt vmcnt(0)
	s_waitcnt vmcnt(0) lgkmcnt(0)
	s_barrier
	s_and_saveexec_b64 s[4:5], s[8:9]
	s_cbranch_execz .LBB0_877
	s_waitcnt vmcnt(0) expcnt(0) lgkmcnt(0)
	s_getreg_b32 s6, hwreg(HW_REG_XCC_ID, 0, 4)
	v_readlane_b32 s14, v254, 42
	v_readlane_b32 s7, v255, 21
	s_and_b32 s6, s6, 15
	v_mov_b32_e32 v2, s14
	ds_read_b32 v3, v2
	ds_read_b32 v4, v2 offset:4
	s_lshl_b32 s6, s6, 8
	s_add_i32 s10, s7, 1
	s_add_u32 s14, s6, 0x5400
	v_mov_b32_e32 v2, s14
	global_atomic_add v5, v2, v222, s[46:47] sc0
	v_writelane_b32 v255, s10, 21
	s_waitcnt lgkmcnt(0)
	v_readfirstlane_b32 s8, v3
	v_readfirstlane_b32 s9, v4
	s_nop 0
	s_mul_i32 s11, s10, s8
	s_mul_i32 s12, s10, s9
	s_waitcnt vmcnt(0)
	v_readfirstlane_b32 s15, v5
	s_nop 0
	s_add_i32 s15, s15, 1
	s_cmp_eq_u32 s15, s11
	s_cbranch_scc0 .Lgb877_local
	buffer_wbl2 sc1
	s_waitcnt vmcnt(0)
	v_mov_b32_e32 v3, 0x7400
	global_atomic_add v5, v3, v222, s[46:47] sc0
	s_waitcnt vmcnt(0)
	v_readfirstlane_b32 s15, v5
	v_mov_b32_e32 v3, 0x7500
	s_add_i32 s15, s15, 1
	s_cmp_eq_u32 s15, s12
	s_cbranch_scc0 .Lgb877_topw
	global_atomic_add v3, v222, s[46:47]
	s_branch .Lgb877_toprel

.Lgb877_done:
.LBB0_877:
	s_or_b64 exec, exec, s[4:5]
	v_readlane_b32 s4, v253, 25
	v_readlane_b32 s5, v253, 26
	s_waitcnt lgkmcnt(0)
	s_barrier
	v_mbcnt_lo_u32_b32 v0, -1, 0
	v_mbcnt_hi_u32_b32 v0, -1, v0
	s_andn2_b64 vcc, exec, s[4:5]
	s_cbranch_vccnz .LBB0_880
	v_lshlrev_b32_e32 v2, 2, v0
	v_ashrrev_i32_e32 v3, 31, v2
	v_readlane_b32 s6, v254, 57
	v_lshlrev_b64 v[66:67], 2, v[2:3]
	v_readlane_b32 s7, v254, 58
	s_load_dwordx2 s[4:5], s[78:79], 0x10
	v_readlane_b32 s10, v254, 37
	v_lshl_add_u64 v[4:5], s[6:7], 0, v[66:67]
	s_mov_b64 s[6:7], 0x1a000
	v_lshl_add_u64 v[68:69], v[4:5], 0, s[6:7]
	s_mov_b64 s[6:7], 0x1c000
	v_lshl_add_u64 v[70:71], v[4:5], 0, s[6:7]
	s_mov_b64 s[6:7], 0x1b000
	v_lshl_add_u64 v[72:73], v[4:5], 0, s[6:7]
	v_readlane_b32 s6, v254, 17
	v_readlane_b32 s7, v254, 18
	v_readlane_b32 s14, v254, 31
	v_readlane_b32 s16, v254, 27
	v_lshl_add_u64 v[74:75], v[2:3], 1, s[6:7]
	v_readlane_b32 s6, v254, 35
	v_readlane_b32 s7, v254, 36
	s_waitcnt lgkmcnt(0)
	s_add_u32 s8, s4, s6
	s_addc_u32 s9, s5, s7
	v_readlane_b32 s4, v254, 29
	v_readlane_b32 s6, v254, 33
	v_readlane_b32 s5, v254, 30
	v_readlane_b32 s7, v254, 34
	v_xor_b32_e32 v92, 4, v2
	v_xor_b32_e32 v93, 8, v2
	v_xor_b32_e32 v94, 16, v2
	v_xor_b32_e32 v95, 32, v2
	v_xor_b32_e32 v96, 64, v2
	v_xor_b32_e32 v97, 0x80, v2
	v_readlane_b32 s11, v254, 38
	v_readlane_b32 s15, v254, 32
	v_readlane_b32 s17, v254, 28
	s_mov_b32 s5, 0x800000
	s_mov_b32 s7, 0xc00000

.LBB0_882:
	s_waitcnt vmcnt(0)
	s_waitcnt lgkmcnt(0)
	s_barrier
	s_and_saveexec_b64 s[4:5], s[8:9]
	s_cbranch_execz .LBB0_926
	s_waitcnt vmcnt(0) expcnt(0) lgkmcnt(0)
	s_getreg_b32 s6, hwreg(HW_REG_XCC_ID, 0, 4)
	v_readlane_b32 s14, v254, 42
	v_readlane_b32 s7, v255, 21
	s_and_b32 s6, s6, 15
	v_mov_b32_e32 v2, s14
	ds_read_b32 v3, v2
	ds_read_b32 v4, v2 offset:4
	s_lshl_b32 s6, s6, 8
	s_add_i32 s10, s7, 1
	s_add_u32 s14, s6, 0x5400
	v_mov_b32_e32 v2, s14
	global_atomic_add v5, v2, v222, s[46:47] sc0
	v_writelane_b32 v255, s10, 21
	s_waitcnt lgkmcnt(0)
	v_readfirstlane_b32 s8, v3
	v_readfirstlane_b32 s9, v4
	s_nop 0
	s_mul_i32 s11, s10, s8
	s_mul_i32 s12, s10, s9
	s_waitcnt vmcnt(0)
	v_readfirstlane_b32 s15, v5
	s_nop 0
	s_add_i32 s15, s15, 1
	s_cmp_eq_u32 s15, s11
	s_cbranch_scc0 .Lgb926_local
	buffer_wbl2 sc1
	s_waitcnt vmcnt(0)
	v_mov_b32_e32 v3, 0x7400
	global_atomic_add v5, v3, v222, s[46:47] sc0
	s_waitcnt vmcnt(0)
	v_readfirstlane_b32 s15, v5
	v_mov_b32_e32 v3, 0x7500
	s_add_i32 s15, s15, 1
	s_cmp_eq_u32 s15, s12
	s_cbranch_scc0 .Lgb926_topw
	global_atomic_add v3, v222, s[46:47]
	s_branch .Lgb926_toprel

.Lgb926_done:
.LBB0_926:
	s_or_b64 exec, exec, s[4:5]
	v_readlane_b32 s4, v254, 47
	v_readlane_b32 s5, v254, 48
	s_and_b64 s[4:5], s[4:5], exec
	s_cselect_b32 s34, 64, 0x44
	s_waitcnt lgkmcnt(0)
	s_barrier
	s_mul_i32 s12, s34, 22
	v_mbcnt_lo_u32_b32 v0, -1, 0
	v_mbcnt_hi_u32_b32 v0, -1, v0
	s_cmp_ge_i32 s2, s12
	s_waitcnt vmcnt(0)
	v_add_u32_e32 v16, s33, v0
	s_nop 0
	v_readfirstlane_b32 s7, v16
	s_cbranch_scc1 .LBB0_942
	v_lshlrev_b32_e32 v0, 4, v16
	v_add_u32_e32 v2, 0x2000, v0
	v_ashrrev_i32_e32 v3, 31, v2
	v_lshrrev_b32_e32 v3, 22, v3
	v_add_u32_e32 v3, v2, v3
	v_ashrrev_i32_e32 v10, 10, v3
	v_mul_i32_i24_e32 v3, 0x400, v10
	v_sub_u32_e32 v2, v2, v3
	v_lshrrev_b32_e32 v3, 4, v2
	v_bitop3_b32 v2, v3, v2, 32 bitop3:0x6c
	v_ashrrev_i32_e32 v3, 31, v2
	v_lshrrev_b32_e32 v3, 26, v3
	v_add_u32_e32 v3, v2, v3
	v_lshlrev_b32_e32 v4, 3, v10
	v_readlane_b32 s4, v254, 51
	v_ashrrev_i32_e32 v11, 6, v3
	v_and_b32_e32 v4, -16, v4
	s_add_u32 s35, s4, 0x500000
	v_readlane_b32 s4, v254, 52
	v_add_u32_e32 v4, v11, v4
	s_addc_u32 s36, s4, 0
	v_and_b32_e32 v5, 3, v11
	s_mov_b32 s4, 0x1fffe0
	v_lshrrev_b32_e32 v6, 2, v4
	v_lshlrev_b32_e32 v7, 1, v4
	v_and_b32_e32 v3, 0xc0, v3
	v_and_or_b32 v5, v4, s4, v5
	v_and_b32_e32 v6, 4, v6
	v_and_b32_e32 v7, 24, v7
	v_sub_u32_e32 v2, v2, v3
	v_or3_b32 v5, v5, v6, v7
	v_lshlrev_b32_e32 v6, 5, v10
	v_ashrrev_i16_sdwa v2, v222, sext(v2) dst_sel:DWORD dst_unused:UNUSED_PAD src0_sel:DWORD src1_sel:BYTE_0
	v_and_b32_e32 v6, 32, v6
	v_bfe_i32 v12, v2, 0, 16
	v_add_lshl_u32 v2, v6, v12, 1
	v_lshl_add_u32 v130, v5, 11, v2
	v_lshl_add_u32 v132, v4, 11, v2
	v_bfe_i32 v2, v16, 27, 1
	v_lshrrev_b32_e32 v2, 22, v2
	v_add_u32_e32 v2, v0, v2
	v_and_b32_e32 v2, 0xfffffc00, v2
	v_sub_u32_e32 v0, v0, v2
	v_lshrrev_b32_e32 v2, 4, v0
	v_ashrrev_i32_e32 v3, 31, v16
	v_bitop3_b32 v0, v2, v0, 32 bitop3:0x6c
	v_lshrrev_b32_e32 v3, 26, v3
	v_ashrrev_i32_e32 v2, 31, v0
	v_add_u32_e32 v3, v16, v3
	v_lshrrev_b32_e32 v2, 26, v2
	v_ashrrev_i32_e32 v14, 6, v3
	v_add_u32_e32 v2, v0, v2
	v_lshlrev_b32_e32 v3, 3, v14
	v_ashrrev_i32_e32 v13, 6, v2
	v_and_b32_e32 v3, -16, v3
	v_add_u32_e32 v3, v13, v3
	v_and_b32_e32 v4, 3, v13
	s_ashr_i32 s6, s7, 6
	v_and_or_b32 v4, v3, s4, v4
	s_lshr_b32 s38, s12, 3
	v_readlane_b32 s4, v253, 52
	s_ashr_i32 s8, s7, 8
	s_lshl_b32 s37, s6, 10
	s_add_i32 s39, s38, 1
	v_readlane_b32 s5, v253, 53
	s_and_b64 s[4:5], s[4:5], exec
	s_cselect_b32 s4, s39, s38
	v_readlane_b32 s5, v253, 54
	s_mul_i32 s4, s4, s5
	v_readlane_b32 s5, v253, 55
	s_add_i32 s4, s4, s5
	s_mul_hi_i32 s5, s4, 0x2e8ba2e9
	s_lshr_b32 s9, s5, 31
	s_ashr_i32 s5, s5, 5
	s_add_i32 s5, s5, s9
	s_lshl_b32 s9, s5, 3
	s_sub_i32 s10, s34, s9
	s_min_i32 s10, s10, 8
	v_and_b32_e32 v2, 0xc0, v2
	s_abs_i32 s11, s10
	v_sub_u32_e32 v0, v0, v2
	v_cvt_f32_u32_e32 v2, s11
	s_sub_i32 s15, 0, s11
	s_mulk_i32 s5, 0xb0
	s_sub_i32 s4, s4, s5
	v_rcp_iflag_f32_e32 v2, v2
	s_abs_i32 s14, s4
	s_xor_b32 s5, s4, s10
	s_ashr_i32 s5, s5, 31
	v_mul_f32_e32 v2, 0x4f7ffffe, v2
	v_cvt_u32_f32_e32 v2, v2
	v_lshrrev_b32_e32 v5, 2, v3
	v_lshlrev_b32_e32 v6, 1, v3
	v_and_b32_e32 v5, 4, v5
	v_readfirstlane_b32 s16, v2
	s_mul_i32 s15, s15, s16
	s_mul_hi_u32 s15, s16, s15
	s_add_i32 s16, s16, s15
	s_mul_hi_u32 s15, s14, s16
	s_mul_i32 s16, s15, s11
	s_sub_i32 s14, s14, s16
	s_add_i32 s16, s15, 1
	s_sub_i32 s17, s14, s11
	s_cmp_ge_u32 s14, s11
	s_cselect_b32 s15, s16, s15
	s_cselect_b32 s14, s17, s14
	s_add_i32 s16, s15, 1
	s_cmp_ge_u32 s14, s11
	s_cselect_b32 s11, s16, s15
	s_xor_b32 s11, s11, s5
	s_sub_i32 s24, s11, s5
	s_mul_i32 s5, s24, s10
	s_sub_i32 s4, s4, s5
	s_add_i32 s26, s9, s4
	v_and_b32_e32 v6, 24, v6
	s_ashr_i32 s27, s26, 31
	s_ashr_i32 s25, s24, 31
	v_or3_b32 v4, v4, v5, v6
	v_lshlrev_b32_e32 v5, 5, v14
	v_ashrrev_i16_sdwa v0, v222, sext(v0) dst_sel:DWORD dst_unused:UNUSED_PAD src0_sel:DWORD src1_sel:BYTE_0
	s_lshl_b64 s[10:11], s[26:27], 19
	s_lshl_b64 s[4:5], s[24:25], 19
	v_and_b32_e32 v5, 32, v5
	v_bfe_i32 v15, v0, 0, 16
	s_add_u32 s4, s35, s4
	v_add_lshl_u32 v5, v5, v15, 1
	s_addc_u32 s5, s36, s5
	s_add_i32 s25, s37, 0
	v_lshl_add_u32 v0, v4, 11, v5
	s_add_i32 m0, s25, 0x10000
	v_readlane_b32 s9, v254, 8
	global_load_lds_dwordx4 v0, s[4:5]
	s_add_i32 m0, s25, 0x12000
	s_add_u32 s14, s4, 0x40000
	global_load_lds_dwordx4 v130, s[4:5]
	s_addc_u32 s15, s5, 0
	s_add_i32 m0, s25, 0x14000
	v_lshl_add_u32 v134, v3, 11, v5
	global_load_lds_dwordx4 v0, s[14:15]
	s_add_i32 m0, s25, 0x16000
	s_add_u32 s28, s9, s10
	v_readlane_b32 s9, v254, 9
	s_addc_u32 s29, s9, s11
	s_add_i32 s27, s25, 0x2000
	global_load_lds_dwordx4 v130, s[14:15]
	s_mov_b32 m0, s25
	s_add_u32 s10, s28, 0x40000
	global_load_lds_dwordx4 v134, s[28:29]
	s_mov_b32 m0, s27
	s_addc_u32 s11, s29, 0
	s_add_i32 s40, s25, 0x4000
	global_load_lds_dwordx4 v132, s[28:29]
	s_mov_b32 m0, s40
	s_add_i32 s41, s25, 0x6000
	global_load_lds_dwordx4 v134, s[10:11]
	s_mov_b32 m0, s41
	v_mov_b32_e32 v131, v1
	global_load_lds_dwordx4 v132, s[10:11]
	v_mov_b32_e32 v135, v1
	v_mov_b32_e32 v133, v1
	s_cmp_eq_u32 s8, 1
	v_lshl_add_u64 v[8:9], s[4:5], 0, v[0:1]
	v_lshl_add_u64 v[6:7], s[4:5], 0, v[130:131]
	v_lshl_add_u64 v[2:3], s[28:29], 0, v[134:135]
	s_cselect_b64 s[10:11], -1, 0
	s_cmp_lg_u32 s8, 1
	v_lshl_add_u64 v[4:5], s[28:29], 0, v[132:133]
	s_cbranch_scc1 .LBB0_929
	s_barrier

.Lgb988_done:
.LBB0_988:
	s_or_b64 exec, exec, s[4:5]
	v_readlane_b32 s4, v254, 51
	s_add_u32 s40, s4, 0x1000000
	v_readlane_b32 s4, v254, 52
	s_addc_u32 s41, s4, 0
	v_readlane_b32 s4, v254, 61
	v_readlane_b32 s5, v254, 62
	s_and_b64 vcc, exec, s[4:5]
	s_mov_b64 s[4:5], -1
	s_waitcnt lgkmcnt(0)
	s_barrier
	s_cbranch_vccnz .LBB0_1210
	v_readlane_b32 s4, v255, 0
	v_mbcnt_lo_u32_b32 v0, -1, 0
	v_mbcnt_hi_u32_b32 v0, -1, v0
	v_readlane_b32 s5, v255, 1
	v_add_u32_e32 v216, s33, v0
	s_and_b64 vcc, exec, s[4:5]
	v_readfirstlane_b32 s12, v216
	s_cbranch_vccnz .LBB0_1096
	v_lshlrev_b32_e32 v0, 4, v216
	v_add_u32_e32 v3, 0x2000, v0
	v_ashrrev_i32_e32 v2, 31, v3
	v_lshrrev_b32_e32 v2, 22, v2
	v_add_u32_e32 v2, v3, v2
	v_ashrrev_i32_e32 v2, 10, v2
	v_mul_i32_i24_e32 v4, 0x400, v2
	v_sub_u32_e32 v3, v3, v4
	v_lshrrev_b32_e32 v4, 4, v3
	v_bitop3_b32 v5, v4, v3, 32 bitop3:0x6c
	v_ashrrev_i32_e32 v3, 31, v5
	v_lshrrev_b32_e32 v3, 26, v3
	v_add_u32_e32 v6, v5, v3
	v_lshlrev_b32_e32 v4, 3, v2
	v_ashrrev_i32_e32 v3, 6, v6
	v_and_b32_e32 v4, -16, v4
	v_add_u32_e32 v7, v3, v4
	v_and_b32_e32 v4, 3, v3
	s_mov_b32 s4, 0xffffe0
	v_lshrrev_b32_e32 v8, 2, v7
	v_lshlrev_b32_e32 v9, 1, v7
	v_and_or_b32 v4, v7, s4, v4
	v_and_b32_e32 v8, 4, v8
	v_and_b32_e32 v9, 24, v9
	v_and_b32_e32 v6, 0xc0, v6
	v_or3_b32 v4, v4, v8, v9
	v_sub_u32_e32 v5, v5, v6
	v_mul_u32_u24_e32 v8, 0xb00, v4
	v_lshlrev_b32_e32 v4, 5, v2
	v_ashrrev_i16_sdwa v5, v222, sext(v5) dst_sel:DWORD dst_unused:UNUSED_PAD src0_sel:DWORD src1_sel:BYTE_0
	v_and_b32_e32 v4, 32, v4
	v_bfe_i32 v5, v5, 0, 16
	s_movk_i32 s5, 0xb00
	v_add_u32_e32 v6, v4, v5
	v_mul_lo_u32 v7, v7, s5
	v_add_lshl_u32 v132, v8, v6, 1
	v_add_lshl_u32 v134, v6, v7, 1
	v_bfe_i32 v6, v216, 27, 1
	v_lshrrev_b32_e32 v6, 22, v6
	v_add_u32_e32 v6, v0, v6
	v_and_b32_e32 v6, 0xfffffc00, v6
	v_sub_u32_e32 v0, v0, v6
	v_lshrrev_b32_e32 v6, 4, v0
	v_ashrrev_i32_e32 v7, 31, v216
	v_bitop3_b32 v0, v6, v0, 32 bitop3:0x6c
	v_lshrrev_b32_e32 v7, 26, v7
	v_ashrrev_i32_e32 v6, 31, v0
	v_add_u32_e32 v7, v216, v7
	v_lshrrev_b32_e32 v6, 26, v6
	v_ashrrev_i32_e32 v7, 6, v7
	v_add_u32_e32 v9, v0, v6
	v_lshlrev_b32_e32 v8, 3, v7
	v_ashrrev_i32_e32 v6, 6, v9
	v_and_b32_e32 v8, -16, v8
	v_add_u32_e32 v10, v6, v8
	v_and_b32_e32 v8, 3, v6
	v_lshrrev_b32_e32 v11, 2, v10
	v_lshlrev_b32_e32 v12, 1, v10
	v_and_or_b32 v8, v10, s4, v8
	v_and_b32_e32 v11, 4, v11
	v_and_b32_e32 v12, 24, v12
	v_and_b32_e32 v9, 0xc0, v9
	s_ashr_i32 s31, s12, 6
	v_or3_b32 v8, v8, v11, v12
	v_sub_u32_e32 v0, v0, v9
	s_ashr_i32 s30, s12, 8
	s_lshl_b32 s15, s31, 10
	v_mul_u32_u24_e32 v11, 0xb00, v8
	v_lshlrev_b32_e32 v8, 5, v7
	v_ashrrev_i16_sdwa v0, v222, sext(v0) dst_sel:DWORD dst_unused:UNUSED_PAD src0_sel:DWORD src1_sel:BYTE_0
	v_readlane_b32 s4, v254, 41
	v_and_b32_e32 v8, 32, v8
	v_bfe_i32 v9, v0, 0, 16
	v_mul_lo_u32 v10, v10, s5
	s_add_u32 s4, s40, s4
	v_readlane_b32 s5, v254, 39
	v_add_u32_e32 v12, v8, v9
	s_addc_u32 s5, s41, s5
	s_add_i32 s26, s15, 0
	v_add_lshl_u32 v0, v11, v12, 1
	s_add_i32 m0, s26, 0x10000
	v_add_lshl_u32 v136, v12, v10, 1
	global_load_lds_dwordx4 v0, s[4:5]
	s_add_i32 m0, s26, 0x12000
	s_add_u32 s6, s4, 0xb0000
	global_load_lds_dwordx4 v132, s[4:5]
	s_addc_u32 s7, s5, 0
	s_add_i32 m0, s26, 0x14000
	s_add_i32 s27, s26, 0x2000
	global_load_lds_dwordx4 v0, s[6:7]
	s_add_i32 m0, s26, 0x16000
	s_add_i32 s28, s26, 0x4000
	global_load_lds_dwordx4 v132, s[6:7]
	v_readlane_b32 s6, v254, 0
	s_mov_b32 m0, s26
	v_readlane_b32 s7, v254, 1
	s_add_i32 s29, s26, 0x6000
	s_cmp_lg_u32 s30, 1
	s_nop 2
	global_load_lds_dwordx4 v136, s[6:7]
	s_mov_b32 m0, s27
	s_nop 0
	global_load_lds_dwordx4 v134, s[6:7]
	v_readlane_b32 s6, v254, 2
	s_mov_b32 m0, s28
	v_readlane_b32 s7, v254, 3
	s_nop 4
	global_load_lds_dwordx4 v136, s[6:7]
	s_mov_b32 m0, s29
	s_nop 0
	global_load_lds_dwordx4 v134, s[6:7]
	s_cbranch_scc1 .LBB0_992
	s_barrier

.LBB0_1116:
	s_waitcnt vmcnt(0)
	s_waitcnt vmcnt(0) lgkmcnt(0)
	s_barrier
	s_and_saveexec_b64 s[4:5], s[6:7]
	s_cbranch_execz .LBB0_1160
	s_waitcnt vmcnt(0) expcnt(0) lgkmcnt(0)
	s_getreg_b32 s6, hwreg(HW_REG_XCC_ID, 0, 4)
	v_readlane_b32 s14, v254, 42
	v_readlane_b32 s7, v255, 21
	s_and_b32 s6, s6, 15
	v_mov_b32_e32 v2, s14
	ds_read_b32 v3, v2
	ds_read_b32 v4, v2 offset:4
	s_lshl_b32 s6, s6, 8
	s_add_i32 s10, s7, 1
	s_add_u32 s14, s6, 0x5400
	v_mov_b32_e32 v2, s14
	global_atomic_add v5, v2, v222, s[46:47] sc0
	v_writelane_b32 v255, s10, 21
	s_waitcnt lgkmcnt(0)
	v_readfirstlane_b32 s8, v3
	v_readfirstlane_b32 s9, v4
	s_nop 0
	s_mul_i32 s11, s10, s8
	s_mul_i32 s12, s10, s9
	s_waitcnt vmcnt(0)
	v_readfirstlane_b32 s15, v5
	s_nop 0
	s_add_i32 s15, s15, 1
	s_cmp_eq_u32 s15, s11
	s_cbranch_scc0 .Lgb1160_local
	buffer_wbl2 sc1
	s_waitcnt vmcnt(0)
	v_mov_b32_e32 v3, 0x7400
	global_atomic_add v5, v3, v222, s[46:47] sc0
	s_waitcnt vmcnt(0)
	v_readfirstlane_b32 s15, v5
	v_mov_b32_e32 v3, 0x7500
	s_add_i32 s15, s15, 1
	s_cmp_eq_u32 s15, s12
	s_cbranch_scc0 .Lgb1160_topw
	global_atomic_add v3, v222, s[46:47]
	s_branch .Lgb1160_toprel

.Lgb1160_done:
.LBB0_1160:
	s_or_b64 exec, exec, s[4:5]
	v_readlane_b32 s4, v253, 25
	v_readlane_b32 s5, v253, 26
	s_waitcnt lgkmcnt(0)
	s_barrier
	v_mbcnt_lo_u32_b32 v0, -1, 0
	v_mbcnt_hi_u32_b32 v0, -1, v0
	s_andn2_b64 vcc, exec, s[4:5]
	s_cbranch_vccnz .LBB0_1163
	v_lshlrev_b32_e32 v2, 2, v0
	v_ashrrev_i32_e32 v3, 31, v2
	v_readlane_b32 s4, v254, 57
	v_lshlrev_b64 v[66:67], 2, v[2:3]
	v_readlane_b32 s5, v254, 58
	v_readlane_b32 s10, v254, 33
	v_readlane_b32 s6, v254, 31
	v_lshl_add_u64 v[4:5], s[4:5], 0, v[66:67]
	s_mov_b64 s[4:5], 0x1d000
	v_lshl_add_u64 v[68:69], v[4:5], 0, s[4:5]
	v_readlane_b32 s4, v253, 44
	v_readlane_b32 s5, v253, 45
	v_readlane_b32 s8, v254, 37
	v_readlane_b32 s11, v254, 34
	v_lshl_add_u64 v[70:71], s[4:5], 0, v[66:67]
	v_readlane_b32 s4, v253, 46
	v_readlane_b32 s5, v253, 47
	v_readlane_b32 s14, v254, 27
	v_xor_b32_e32 v0, 4, v2
	v_lshl_add_u64 v[72:73], s[4:5], 0, v[66:67]
	v_readlane_b32 s4, v254, 17
	v_readlane_b32 s5, v254, 18
	v_xor_b32_e32 v78, 8, v2
	v_xor_b32_e32 v79, 16, v2
	v_lshl_add_u64 v[74:75], v[2:3], 1, s[4:5]
	v_readlane_b32 s4, v254, 29
	v_readlane_b32 s5, v254, 30
	v_xor_b32_e32 v80, 32, v2
	v_xor_b32_e32 v81, 64, v2
	v_xor_b32_e32 v82, 0x80, v2
	v_readlane_b32 s7, v254, 32
	v_readlane_b32 s9, v254, 38
	v_readlane_b32 s15, v254, 28
	s_mov_b32 s5, 0x800000
	s_mov_b32 s11, 0xc00000

.LBB0_1165:
	s_waitcnt vmcnt(0)
	s_barrier
	s_and_saveexec_b64 s[4:5], s[6:7]
	s_cbranch_execz .LBB0_1209
	s_waitcnt vmcnt(0) expcnt(0) lgkmcnt(0)
	s_getreg_b32 s6, hwreg(HW_REG_XCC_ID, 0, 4)
	v_readlane_b32 s14, v254, 42
	v_readlane_b32 s7, v255, 21
	s_and_b32 s6, s6, 15
	v_mov_b32_e32 v2, s14
	ds_read_b32 v3, v2
	ds_read_b32 v4, v2 offset:4
	s_lshl_b32 s6, s6, 8
	s_add_i32 s10, s7, 1
	s_add_u32 s14, s6, 0x5400
	v_mov_b32_e32 v2, s14
	global_atomic_add v5, v2, v222, s[46:47] sc0
	v_writelane_b32 v255, s10, 21
	s_waitcnt lgkmcnt(0)
	v_readfirstlane_b32 s8, v3
	v_readfirstlane_b32 s9, v4
	s_nop 0
	s_mul_i32 s11, s10, s8
	s_mul_i32 s12, s10, s9
	s_waitcnt vmcnt(0)
	v_readfirstlane_b32 s15, v5
	s_nop 0
	s_add_i32 s15, s15, 1
	s_cmp_eq_u32 s15, s11
	s_cbranch_scc0 .Lgb1209_local
	buffer_wbl2 sc1
	s_waitcnt vmcnt(0)
	v_mov_b32_e32 v3, 0x7400
	global_atomic_add v5, v3, v222, s[46:47] sc0
	s_waitcnt vmcnt(0)
	v_readfirstlane_b32 s15, v5
	v_mov_b32_e32 v3, 0x7500
	s_add_i32 s15, s15, 1
	s_cmp_eq_u32 s15, s12
	s_cbranch_scc0 .Lgb1209_topw
	global_atomic_add v3, v222, s[46:47]
	s_branch .Lgb1209_toprel

.Lgb1209_done:
.LBB0_1209:
	s_or_b64 exec, exec, s[4:5]
	s_mov_b64 s[4:5], 0
	s_waitcnt lgkmcnt(0)
	s_barrier
